# FINAL norm loop: gamma quads loaded once, the four x loads of a row issued together (one round trip per row instead of eight)
# baseline (speedup 1.0000x reference)
.LBB0_1174:
	s_andn2_b64 vcc, exec, s[0:1]
	s_cbranch_vccnz .LBB0_1179
	s_add_i32 s0, s91, 0x20150
	v_mov_b32_e32 v0, s0
	ds_read_b32 v0, v0
	s_add_i32 s1, s91, 0x20154
	v_readlane_b32 s2, v254, 20
	s_cmpk_gt_i32 s2, 0x3fff
	v_readlane_b32 s3, v254, 21
	s_waitcnt lgkmcnt(0)
	v_readfirstlane_b32 s0, v0
	v_mov_b32_e32 v0, s1
	ds_read_b32 v0, v0
	s_waitcnt lgkmcnt(0)
	v_readfirstlane_b32 s1, v0
	s_cbranch_scc1 .LBB0_1179
	v_lshlrev_b32_e32 v152, 4, v164
	v_lshl_add_u64 v[12:13], s[0:1], 0, v[152:153]
	v_readlane_b32 s0, v254, 20
	s_mov_b32 s6, s0
	v_readlane_b32 s8, v254, 22
	v_readlane_b32 s1, v254, 21
	s_ashr_i32 s7, s0, 31
	v_readlane_b32 s9, v254, 23
	s_mov_b32 s4, s6
	s_lshl_b64 s[0:1], s[6:7], 12
	s_ashr_i32 s9, s8, 31
	v_writelane_b32 v254, s4, 20
	s_add_i32 s2, s91, 0x20158
	s_add_i32 s3, s91, 0x2015c
	v_lshl_or_b32 v14, v164, 4, s0
	v_mov_b32_e32 v15, s1
	s_lshl_b64 s[0:1], s[8:9], 12
	v_writelane_b32 v254, s5, 21
	s_mov_b32 s4, s6
	global_load_dwordx4 v[28:31], v[12:13], off
	global_load_dwordx4 v[32:35], v[12:13], off offset:1024
	global_load_dwordx4 v[36:39], v[12:13], off offset:2048
	global_load_dwordx4 v[40:43], v[12:13], off offset:3072
.LBB0_1177:
	s_nop 0
	v_mov_b32_e32 v0, s2
	ds_read_b32 v0, v0
	s_add_i32 s4, s4, s8
	s_cmpk_gt_i32 s4, 0x3fff
	s_waitcnt lgkmcnt(0)
	v_readfirstlane_b32 s6, v0
	v_mov_b32_e32 v0, s3
	ds_read_b32 v0, v0
	s_waitcnt lgkmcnt(0)
	v_readfirstlane_b32 s7, v0
	s_nop 1
	v_lshl_add_u64 v[16:17], s[6:7], 0, v[14:15]
	global_load_dwordx4 v[18:21], v[16:17], off
	global_load_dwordx4 v[0:3], v[16:17], off offset:1024
	global_load_dwordx4 v[4:7], v[16:17], off offset:2048
	global_load_dwordx4 v[8:11], v[16:17], off offset:3072
	v_lshl_add_u64 v[14:15], v[14:15], 0, s[0:1]
	s_waitcnt vmcnt(3)
	v_mul_f32_e32 v60, v19, v19
	v_mul_f32_e32 v61, v21, v21
	v_fmac_f32_e32 v60, v18, v18
	v_fmac_f32_e32 v61, v20, v20
	v_add_f32_e32 v62, v60, v61
	s_waitcnt vmcnt(2)
	v_mul_f32_e32 v60, v1, v1
	v_mul_f32_e32 v61, v3, v3
	v_fmac_f32_e32 v60, v0, v0
	v_fmac_f32_e32 v61, v2, v2
	v_add_f32_e32 v60, v60, v61
	v_add_f32_e32 v62, v62, v60
	s_waitcnt vmcnt(1)
	v_mul_f32_e32 v60, v5, v5
	v_mul_f32_e32 v61, v7, v7
	v_fmac_f32_e32 v60, v4, v4
	v_fmac_f32_e32 v61, v6, v6
	v_add_f32_e32 v60, v60, v61
	v_add_f32_e32 v22, v62, v60
	s_waitcnt vmcnt(0)
	v_mul_f32_e32 v23, v9, v9
	v_mul_f32_e32 v24, v11, v11
	v_fmac_f32_e32 v23, v8, v8
	v_fmac_f32_e32 v24, v10, v10
	v_add_f32_e32 v23, v23, v24
	v_add_f32_e32 v22, v22, v23
	s_nop 1
	v_add_f32_dpp v22, v22, v22 quad_perm:[1,0,3,2] row_mask:0xf bank_mask:0xf bound_ctrl:1
	s_nop 1
	v_add_f32_dpp v22, v22, v22 quad_perm:[2,3,0,1] row_mask:0xf bank_mask:0xf bound_ctrl:1
	s_nop 1
	v_add_f32_dpp v22, v22, v22 row_half_mirror row_mask:0xf bank_mask:0xf bound_ctrl:1
	s_nop 1
	v_add_f32_dpp v22, v22, v22 row_mirror row_mask:0xf bank_mask:0xf bound_ctrl:1
	v_mov_b32_e32 v23, v22
	s_nop 1
	v_permlane16_swap_b32 v22, v23
	s_nop 1
	s_nop 0
	v_add_f32_e32 v22, v22, v23
	v_mov_b32_e32 v23, v22
	s_nop 1
	v_permlane32_swap_b32 v22, v23
	s_nop 1
	s_nop 0
	v_add_f32_e32 v22, v22, v23
	v_fmamk_f32 v22, v22, 0x3a800000, v226
	v_cmp_gt_f32_e32 vcc, s82, v22
	v_mul_f32_e32 v23, 0x4b800000, v22
	s_nop 0
	v_cndmask_b32_e32 v22, v22, v23, vcc
	v_rsq_f32_e32 v22, v22
	s_nop 0
	v_mul_f32_e32 v23, 0x45800000, v22
	v_cndmask_b32_e32 v22, v22, v23, vcc
	v_pk_mul_f32 v[24:25], v[18:19], v[22:23] op_sel_hi:[1,0]
	v_pk_mul_f32 v[26:27], v[20:21], v[22:23] op_sel_hi:[1,0]
	v_pk_mul_f32 v[44:45], v[28:29], v[24:25]
	v_pk_mul_f32 v[46:47], v[30:31], v[26:27]
	global_store_dwordx4 v[16:17], v[44:47], off
	v_pk_mul_f32 v[24:25], v[0:1], v[22:23] op_sel_hi:[1,0]
	v_pk_mul_f32 v[26:27], v[2:3], v[22:23] op_sel_hi:[1,0]
	v_pk_mul_f32 v[48:49], v[32:33], v[24:25]
	v_pk_mul_f32 v[50:51], v[34:35], v[26:27]
	global_store_dwordx4 v[16:17], v[48:51], off offset:1024
	v_pk_mul_f32 v[24:25], v[4:5], v[22:23] op_sel_hi:[1,0]
	v_pk_mul_f32 v[26:27], v[6:7], v[22:23] op_sel_hi:[1,0]
	v_pk_mul_f32 v[52:53], v[36:37], v[24:25]
	v_pk_mul_f32 v[54:55], v[38:39], v[26:27]
	global_store_dwordx4 v[16:17], v[52:55], off offset:2048
	v_pk_mul_f32 v[24:25], v[8:9], v[22:23] op_sel_hi:[1,0]
	v_pk_mul_f32 v[26:27], v[10:11], v[22:23] op_sel_hi:[1,0]
	v_pk_mul_f32 v[56:57], v[40:41], v[24:25]
	v_pk_mul_f32 v[58:59], v[42:43], v[26:27]
	global_store_dwordx4 v[16:17], v[56:59], off offset:3072
	s_cbranch_scc0 .LBB0_1177
	v_writelane_b32 v254, s8, 22
	s_nop 1
	v_writelane_b32 v254, s9, 23
